# P7 epilogue: cache the 8 per-row rms scales in VGPRs across tiles of the same row block (recompute only when pm changes)
# speedup vs baseline: 1.0096x; 1.0042x over previous
; #define PG8_BAR __builtin_amdgcn_s_barrier()
;     __device__ bool next(int i, Unit& u) const {
;         if ((long)i * G + c >= nwg) return false;
;         const long L = (long)(rev ? (nwg / G - 1 - i) : i) * G + c;
;         int wgid = (int)L; { const int q = nwg / NXCD, r = nwg % NXCD, xcd = wgid % NXCD, off = wgid / NXCD; wgid = (xcd < r ? xcd * (q + 1) : r * (q + 1) + (xcd - r) * q) + off; }
;         const int nig = WGM * nN, gid = wgid / nig, fm = gid * WGM, gsz = (nM - fm) < WGM ? (nM - fm) : WGM;
; template <class Epi>
; __device__ __forceinline__ void gemm_phase(LAS unsigned char* lds, const Gemm g, const StaticOrder& S, const Epi& E) {
;     int tid = threadIdx.x; asm volatile("" : "+v"(tid));
;     const int wid = __builtin_amdgcn_readfirstlane(tid >> 6), lane = tid & 63, wr = wid >> 2, wc = wid & 3, fr = lane & 15, fq = lane >> 4;
;     const int K = g.K, nt = K / BK, lda = g.lda;
;     unsigned voffA[2], voffB[2];
; #pragma unroll
;     for (int i = 0; i < 2; ++i) { int R, C; stage_rc(tid * 16 + i * 8192, R, C); const int Rb = Epi::PERM ? ((R & ~31) + perm32(R & 31)) : R;
;         voffA[i] = (unsigned)(R * lda + C) * 2u; voffB[i] = (unsigned)(Rb * K + C) * 2u; }
;     const size_t kstep = (size_t)(BK * 2);
;     const size_t hstepA = (size_t)HALF * lda * 2, hstepB = (size_t)HALF * K * 2;
;     const size_t tstepA = 2 * hstepA, tstepB = 2 * hstepB;
;     const unsigned ldsw = (unsigned)wid * 1024u;
;     const int aoff = lds_byte(wr * 64 + fr, fq * 8), boff = lds_byte(wc * 32 + fr, fq * 8);
;     ...
;     Unit cur, nxt; int ui = 0;
;     if (!S.next(0, cur)) return;
;     f32x4 acc[2][2][4][2];
; #pragma unroll
;     for (int a = 0; a < 2; ++a)
; #pragma unroll
;         for (int b = 0; b < 2; ++b)
; #pragma unroll
;             for (int m = 0; m < 4; ++m)
; #pragma unroll
;                 for (int n = 0; n < 2; ++n) acc[a][b][m][n] = (f32x4){0.f, 0.f, 0.f, 0.f};
;     bf16x8 At[4][2], B0[2][2], B1[2][2];
;     const size_t aslab = g.aslab ? g.aslab : 32 * tstepA;
;     const char* cA = (const char*)g.A + (size_t)(cur.pm >> 5) * aslab + (size_t)(cur.pm & 31) * tstepA; const char* cB = (const char*)g.Bt + (size_t)cur.pn * tstepB;
;     PG8_STAGE(PG8_SB(0, 0), cB, voffB); PG8_STAGE(PG8_SB(0, 1), cB + hstepB, voffB); PG8_STAGE(PG8_SA(0, 0), cA, voffA); PG8_STAGE(PG8_SA(0, 1), cA + hstepA, voffA);
;     if (wr == 1) PG8_BAR;
.LBB0_920:
	v_mov_b32_e32 v248, -1
	v_readlane_b32 s0, v235, 46
	v_mov_b32_e32 v10, v196
	v_readlane_b32 s1, v235, 47
	s_waitcnt lgkmcnt(0)
	s_andn2_b64 vcc, exec, s[0:1]
	v_readfirstlane_b32 s5, v10
	s_cbranch_vccnz .LBB0_936
	v_lshlrev_b32_e32 v0, 4, v10
	v_add_u32_e32 v1, 0x2000, v0
	v_ashrrev_i32_e32 v2, 31, v1
	v_lshrrev_b32_e32 v2, 22, v2
	v_add_u32_e32 v2, v1, v2
	v_ashrrev_i32_e32 v8, 10, v2
	v_mul_i32_i24_e32 v2, 0x400, v8
	v_sub_u32_e32 v1, v1, v2
	v_lshrrev_b32_e32 v2, 4, v1
	v_bitop3_b32 v1, v2, v1, 32 bitop3:0x6c
	v_ashrrev_i32_e32 v2, 31, v1
	v_lshrrev_b32_e32 v2, 26, v2
	v_add_u32_e32 v2, v1, v2
	v_lshlrev_b32_e32 v3, 3, v8
	v_ashrrev_i32_e32 v9, 6, v2
	v_and_b32_e32 v3, -16, v3
	v_add_u32_e32 v3, v9, v3
	v_and_b32_e32 v4, 3, v9
	s_mov_b32 s0, 0x1fffe0
	v_lshrrev_b32_e32 v5, 2, v3
	v_lshlrev_b32_e32 v6, 1, v3
	v_and_b32_e32 v2, 0xc0, v2
	v_and_or_b32 v4, v3, s0, v4
	v_and_b32_e32 v5, 4, v5
	v_and_b32_e32 v6, 24, v6
	v_sub_u32_e32 v1, v1, v2
	v_mov_b32_e32 v2, 1
	v_or3_b32 v4, v4, v5, v6
	v_lshlrev_b32_e32 v5, 5, v8
	v_ashrrev_i16_sdwa v1, v2, sext(v1) dst_sel:DWORD dst_unused:UNUSED_PAD src0_sel:DWORD src1_sel:BYTE_0
	v_and_b32_e32 v5, 32, v5
	v_bfe_i32 v11, v1, 0, 16
	v_add_lshl_u32 v1, v5, v11, 1
	v_lshl_add_u32 v128, v4, 11, v1
	v_lshl_add_u32 v130, v3, 11, v1
	v_bfe_i32 v1, v10, 27, 1
	v_lshrrev_b32_e32 v1, 22, v1
	v_add_u32_e32 v1, v0, v1
	v_and_b32_e32 v1, 0xfffffc00, v1
	v_sub_u32_e32 v0, v0, v1
	v_lshrrev_b32_e32 v1, 4, v0
	v_ashrrev_i32_e32 v3, 31, v10
	v_bitop3_b32 v0, v1, v0, 32 bitop3:0x6c
	v_lshrrev_b32_e32 v3, 26, v3
	v_ashrrev_i32_e32 v1, 31, v0
	v_add_u32_e32 v3, v10, v3
	v_lshrrev_b32_e32 v1, 26, v1
	v_ashrrev_i32_e32 v13, 6, v3
	v_add_u32_e32 v1, v0, v1
	v_lshlrev_b32_e32 v3, 3, v13
	v_ashrrev_i32_e32 v12, 6, v1
	v_and_b32_e32 v3, -16, v3
	v_readlane_b32 s2, v235, 0
	v_add_u32_e32 v3, v12, v3
	v_and_b32_e32 v4, 3, v12
	s_ashr_i32 s12, s2, 31
	v_and_or_b32 v4, v3, s0, v4
	s_lshr_b32 s0, s12, 29
	s_add_i32 s0, s2, s0
	s_ashr_i32 s6, s5, 6
	s_ashr_i32 s1, s0, 3
	s_and_b32 s0, s0, -8
	s_ashr_i32 s7, s5, 8
	s_lshl_b32 s20, s6, 10
	s_sub_i32 s0, s2, s0
	s_cmp_lt_i32 s0, 0
	s_movk_i32 s21, 0x2c1
	s_cselect_b32 s2, s21, 0x2c0
	s_mul_i32 s0, s0, s2
	s_add_i32 s0, s0, s1
	s_mul_hi_i32 s1, s0, 0x2e8ba2e9
	s_lshr_b32 s2, s1, 31
	s_ashr_i32 s1, s1, 5
	s_add_i32 s1, s1, s2
	s_lshl_b32 s2, s1, 3
	s_mulk_i32 s1, 0xb0
	s_sub_i32 s0, s0, s1
	s_bfe_u32 s1, s0, 0x3001c
	s_add_i32 s1, s0, s1
	s_and_b32 s3, s1, 0xfff8
	s_sub_i32 s0, s0, s3
	s_sext_i32_i16 s0, s0
	s_add_i32 s41, s2, s0
	s_sext_i32_i16 s0, s1
	v_lshrrev_b32_e32 v5, 2, v3
	v_lshlrev_b32_e32 v6, 1, v3
	v_and_b32_e32 v1, 0xc0, v1
	s_lshr_b32 s4, s0, 3
	s_ashr_i32 s0, s41, 5
	s_lshl_b32 s2, s41, 19
	v_and_b32_e32 v5, 4, v5
	v_and_b32_e32 v6, 24, v6
	v_sub_u32_e32 v0, v0, v1
	s_ashr_i32 s1, s0, 31
	s_and_b32 s8, s2, 0xf80000
	s_bfe_i64 s[2:3], s[4:5], 0x100000
	v_or3_b32 v4, v4, v5, v6
	v_lshlrev_b32_e32 v5, 5, v13
	v_ashrrev_i16_sdwa v0, v2, sext(v0) dst_sel:DWORD dst_unused:UNUSED_PAD src0_sel:DWORD src1_sel:BYTE_0
	s_lshl_b64 s[0:1], s[0:1], 24
	s_lshl_b64 s[2:3], s[2:3], 19
	v_readlane_b32 s14, v235, 31
	v_and_b32_e32 v5, 32, v5
	v_bfe_i32 v14, v0, 0, 16
	v_readlane_b32 s15, v235, 32
	s_add_u32 s2, s14, s2
	v_add_lshl_u32 v0, v5, v14, 1
	s_addc_u32 s3, s15, s3
	s_add_i32 s22, s20, 0
	v_lshl_add_u32 v132, v4, 11, v0
	s_add_i32 m0, s22, 0x10000
	v_readlane_b32 s14, v235, 38
	global_load_lds_dwordx4 v132, s[2:3]
	s_add_i32 m0, s22, 0x12000
	v_readlane_b32 s15, v235, 39
	s_add_u32 s9, s14, s0
	s_addc_u32 s13, s15, s1
	s_add_u32 s0, s2, 0x40000
	global_load_lds_dwordx4 v128, s[2:3]
	s_addc_u32 s1, s3, 0
	s_add_i32 m0, s22, 0x14000
	v_lshl_add_u32 v134, v3, 11, v0
	global_load_lds_dwordx4 v132, s[0:1]
	s_add_i32 m0, s22, 0x16000
	s_add_u32 s16, s9, s8
	s_addc_u32 s17, s13, 0
	s_add_i32 s23, s22, 0x2000
	global_load_lds_dwordx4 v128, s[0:1]
	s_mov_b32 m0, s22
	s_add_u32 s0, s16, 0x40000
	global_load_lds_dwordx4 v134, s[16:17]
	s_mov_b32 m0, s23
	s_addc_u32 s1, s17, 0
	s_add_i32 s24, s22, 0x4000
	global_load_lds_dwordx4 v130, s[16:17]
	s_mov_b32 m0, s24
	s_add_i32 s25, s22, 0x6000
	global_load_lds_dwordx4 v134, s[0:1]
	s_mov_b32 m0, s25
	v_mov_b32_e32 v137, 0
	global_load_lds_dwordx4 v130, s[0:1]
	v_mov_b32_e32 v133, v137
	v_mov_b32_e32 v129, v137
	v_mov_b32_e32 v135, v137
	v_mov_b32_e32 v131, v137
	s_cmp_eq_u32 s7, 1
	s_movk_i32 s26, 0x2000
	s_mov_b32 s27, 0
	v_lshl_add_u64 v[6:7], s[2:3], 0, v[132:133]
	v_lshl_add_u64 v[2:3], s[2:3], 0, v[128:129]
	s_mov_b32 s28, 0x16000
	v_lshl_add_u64 v[0:1], s[16:17], 0, v[134:135]
	s_cselect_b64 s[0:1], -1, 0
	s_cmp_lg_u32 s7, 1
	v_lshl_add_u64 v[4:5], s[16:17], 0, v[130:131]
	s_cbranch_scc1 .LBB0_923
	s_barrier

; template <int NP> __device__ __forceinline__ void load_rs(const float* ssp, int row0, int fq, float (&rs)[2][4]) {
;     ...
;             for (int m = 0; m < 4; ++m) p[ai][m] = *(const f32x4*)(ssp + (size_t)(row0 + ai * HALF + m * 16) * 16 + 4 * fq);
; #pragma unroll
;         for (int ai = 0; ai < 2; ++ai)
; #pragma unroll
;             for (int m = 0; m < 4; ++m) { float s = (p[ai][m][0] + p[ai][m][1]) + (p[ai][m][2] + p[ai][m][3]); s += __shfl_xor(s, 16); s += __shfl_xor(s, 32); rs[ai][m] = s; }
;     }
; #pragma unroll
;     for (int ai = 0; ai < 2; ++ai)
; #pragma unroll
;         for (int m = 0; m < 4; ++m) rs[ai][m] = __builtin_amdgcn_rsqf(rs[ai][m] * (1.0f / D_MODEL) + RMS_EPS);
;     __device__ __forceinline__ void operator()(const f32x4 (&acc)[2][2][4][2], const Unit& u, int wr, int wc, int fr, int fq) const {
;     ...
;                     const f32x4 ga = acc[ai][0][m][q >> 1], ua = acc[ai][1][m][q >> 1]; const int e0 = 2 * (q & 1);
;                     const f32x2 g = (f32x2){ga[e0], ga[e0 + 1]}, up = (f32x2){ua[e0], ua[e0 + 1]};
;                     const f32x2 t = g * nrl; f32x2 ex; ex.x = __builtin_amdgcn_exp2f(t.x); ex.y = __builtin_amdgcn_exp2f(t.y);
;                     const f32x2 d = ex + 1.0f; f32x2 rc; rc.x = __builtin_amdgcn_rcpf(d.x); rc.y = __builtin_amdgcn_rcpf(d.y);
;                     const f32x2 o = (g * up) * (rc * r2);
.LBB0_932:
	v_cmp_eq_u32_e32 vcc, s41, v248
	s_cbranch_vccnz rsc_hit_1
	s_lshl_b32 s2, s41, 8
	s_add_i32 s2, s2, s29
	v_or_b32_e32 v146, s2, v150
	v_ashrrev_i32_e32 v147, 31, v146
	v_or_b32_e32 v160, 16, v146
	v_lshlrev_b64 v[148:149], 6, v[146:147]
	v_ashrrev_i32_e32 v161, 31, v160
	v_or_b32_e32 v168, 32, v146
	v_or_b32_e32 v170, 48, v146
	v_add_u32_e32 v146, 0x80, v146
	v_lshlrev_b64 v[160:161], 6, v[160:161]
	v_ashrrev_i32_e32 v169, 31, v168
	v_ashrrev_i32_e32 v171, 31, v170
	v_ashrrev_i32_e32 v147, 31, v146
	v_lshl_add_u64 v[148:149], v[138:139], 0, v[148:149]
	v_lshl_add_u64 v[164:165], v[138:139], 0, v[160:161]
	v_lshlrev_b64 v[168:169], 6, v[168:169]
	v_lshlrev_b64 v[170:171], 6, v[170:171]
	v_lshlrev_b64 v[176:177], 6, v[146:147]
	global_load_dwordx4 v[160:163], v[148:149], off
	s_nop 0
	global_load_dwordx4 v[164:167], v[164:165], off
	v_lshl_add_u64 v[168:169], v[138:139], 0, v[168:169]
	v_lshl_add_u64 v[172:173], v[138:139], 0, v[170:171]
	v_lshl_add_u64 v[176:177], v[138:139], 0, v[176:177]
	global_load_dwordx4 v[168:171], v[168:169], off
	s_nop 0
	global_load_dwordx4 v[172:175], v[172:173], off
	v_add_co_u32_e32 v148, vcc, s26, v148
	global_load_dwordx4 v[176:179], v[176:177], off
	s_nop 0
	v_addc_co_u32_e32 v149, vcc, 0, v149, vcc
	global_load_dwordx4 v[180:183], v[148:149], off offset:1024
	global_load_dwordx4 v[184:187], v[148:149], off offset:2048
	global_load_dwordx4 v[190:193], v[148:149], off offset:3072
	v_and_b32_e32 v147, 64, v156
	v_xor_b32_e32 v136, 16, v156
	v_add_u32_e32 v147, 64, v147
	v_xor_b32_e32 v149, 32, v156
	v_cmp_lt_i32_e32 vcc, v136, v147
	v_pk_mul_f32 v[120:121], v[124:125], v[120:121]
	v_pk_mul_f32 v[122:123], v[126:127], v[122:123]
	v_cndmask_b32_e32 v136, v156, v136, vcc
	v_cmp_lt_i32_e32 vcc, v149, v147
	v_lshlrev_b32_e32 v136, 2, v136
	v_pk_mul_f32 v[112:113], v[116:117], v[112:113]
	v_cndmask_b32_e32 v147, v156, v149, vcc
	v_lshlrev_b32_e32 v147, 2, v147
	v_pk_mul_f32 v[114:115], v[118:119], v[114:115]
	v_pk_mul_f32 v[104:105], v[108:109], v[104:105]
	s_ashr_i32 s3, s2, 13
	s_mul_hi_i32 s11, s3, 0x4400000
	s_mul_i32 s3, s3, 0x4400000
	v_readlane_b32 s16, v235, 44
	v_lshl_or_b32 v148, s42, 7, v152
	v_readlane_b32 s17, v235, 45
	v_pk_mul_f32 v[106:107], v[110:111], v[106:107]
	v_pk_mul_f32 v[96:97], v[100:101], v[96:97]
	v_pk_mul_f32 v[98:99], v[102:103], v[98:99]
	v_pk_mul_f32 v[88:89], v[92:93], v[88:89]
	v_pk_mul_f32 v[90:91], v[94:95], v[90:91]
	v_pk_mul_f32 v[80:81], v[84:85], v[80:81]
	v_pk_mul_f32 v[82:83], v[86:87], v[82:83]
	v_pk_mul_f32 v[72:73], v[76:77], v[72:73]
	v_pk_mul_f32 v[74:75], v[78:79], v[74:75]
	v_pk_mul_f32 v[64:65], v[68:69], v[64:65]
	v_pk_mul_f32 v[66:67], v[70:71], v[66:67]
	v_pk_mul_f32 v[56:57], v[60:61], v[56:57]
	v_pk_mul_f32 v[58:59], v[62:63], v[58:59]
	v_pk_mul_f32 v[48:49], v[52:53], v[48:49]
	v_pk_mul_f32 v[50:51], v[54:55], v[50:51]
	v_pk_mul_f32 v[40:41], v[44:45], v[40:41]
	v_pk_mul_f32 v[42:43], v[46:47], v[42:43]
	v_pk_mul_f32 v[32:33], v[36:37], v[32:33]
	v_pk_mul_f32 v[34:35], v[38:39], v[34:35]
	v_pk_mul_f32 v[24:25], v[28:29], v[24:25]
	v_pk_mul_f32 v[26:27], v[30:31], v[26:27]
	v_pk_mul_f32 v[16:17], v[20:21], v[16:17]
	v_pk_mul_f32 v[18:19], v[22:23], v[18:19]
	v_pk_mul_f32 v[8:9], v[12:13], v[8:9]
	v_pk_mul_f32 v[10:11], v[14:15], v[10:11]
	v_pk_mul_f32 v[0:1], v[4:5], v[0:1]
	v_pk_mul_f32 v[2:3], v[6:7], v[2:3]
	s_waitcnt vmcnt(0)
	v_mov_b32_e32 v194, v161
	v_mov_b32_e32 v195, v162
	v_mov_b32_e32 v161, v163
	v_pk_add_f32 v[160:161], v[194:195], v[160:161]
	v_mov_b32_e32 v162, v165
	v_mov_b32_e32 v163, v166
	v_mov_b32_e32 v165, v167
	v_mov_b32_e32 v166, v169
	v_mov_b32_e32 v167, v170
	v_mov_b32_e32 v169, v171
	v_mov_b32_e32 v170, v173
	v_mov_b32_e32 v171, v174
	v_mov_b32_e32 v173, v175
	v_mov_b32_e32 v174, v177
	v_mov_b32_e32 v175, v178
	v_mov_b32_e32 v177, v179
	v_add_f32_e32 v149, v160, v161
	v_pk_add_f32 v[160:161], v[162:163], v[164:165]
	v_pk_add_f32 v[162:163], v[166:167], v[168:169]
	v_pk_add_f32 v[166:167], v[174:175], v[176:177]
	v_add_f32_e32 v160, v160, v161
	v_add_f32_e32 v161, v162, v163
	v_mov_b32_e32 v236, v149
	v_mov_b32_e32 v237, v149
	s_nop 1
	v_permlane16_swap_b32_e32 v236, v237
	v_cndmask_b32_e64 v159, v237, v236, s[98:99]
	v_add_f32_e32 v163, v166, v167
	v_mov_b32_e32 v236, v160
	v_mov_b32_e32 v237, v160
	s_nop 1
	v_permlane16_swap_b32_e32 v236, v237
	v_cndmask_b32_e64 v166, v237, v236, s[98:99]
	v_mov_b32_e32 v236, v161
	v_mov_b32_e32 v237, v161
	s_nop 1
	v_permlane16_swap_b32_e32 v236, v237
	v_cndmask_b32_e64 v167, v237, v236, s[98:99]
	v_mov_b32_e32 v178, v181
	s_waitcnt lgkmcnt(2)
	v_add_f32_e32 v149, v149, v159
	v_mov_b32_e32 v236, v149
	v_mov_b32_e32 v237, v149
	s_nop 1
	v_permlane32_swap_b32_e32 v236, v237
	v_cndmask_b32_e64 v159, v237, v236, s[100:101]
	s_waitcnt lgkmcnt(2)
	v_add_f32_e32 v160, v160, v166
	s_waitcnt lgkmcnt(1)
	v_add_f32_e32 v161, v161, v167
	v_mov_b32_e32 v236, v160
	v_mov_b32_e32 v237, v160
	s_nop 1
	v_permlane32_swap_b32_e32 v236, v237
	v_cndmask_b32_e64 v166, v237, v236, s[100:101]
	v_mov_b32_e32 v236, v161
	v_mov_b32_e32 v237, v161
	s_nop 1
	v_permlane32_swap_b32_e32 v236, v237
	v_cndmask_b32_e64 v167, v237, v236, s[100:101]
	v_mov_b32_e32 v179, v182
	v_mov_b32_e32 v181, v183
	v_mov_b32_e32 v182, v185
	v_mov_b32_e32 v183, v186
	v_mov_b32_e32 v185, v187
	v_mov_b32_e32 v186, v191
	v_mov_b32_e32 v187, v192
	v_mov_b32_e32 v191, v193
	v_pk_add_f32 v[164:165], v[170:171], v[172:173]
	v_pk_add_f32 v[168:169], v[178:179], v[180:181]
	v_pk_add_f32 v[170:171], v[182:183], v[184:185]
	s_waitcnt lgkmcnt(2)
	v_add_f32_e32 v149, v149, v159
	s_waitcnt lgkmcnt(1)
	v_add_f32_e32 v159, v160, v166
	s_waitcnt lgkmcnt(0)
; template <int NP> __device__ __forceinline__ void load_rs(const float* ssp, int row0, int fq, float (&rs)[2][4]) {
;     ...
;             for (int m = 0; m < 4; ++m) { float s = (p[ai][m][0] + p[ai][m][1]) + (p[ai][m][2] + p[ai][m][3]); s += __shfl_xor(s, 16); s += __shfl_xor(s, 32); rs[ai][m] = s; }
;     }
; #pragma unroll
;     for (int ai = 0; ai < 2; ++ai)
; #pragma unroll
;         for (int m = 0; m < 4; ++m) rs[ai][m] = __builtin_amdgcn_rsqf(rs[ai][m] * (1.0f / D_MODEL) + RMS_EPS);
;     __device__ __forceinline__ void operator()(const f32x4 (&acc)[2][2][4][2], const Unit& u, int wr, int wc, int fr, int fq) const {
;         const int row0 = u.pm * BM + wr * 64 + fr, col0 = u.pn * HALF + wc * 32 + 8 * fq;
;         float rs[2][4]; load_rs<NP>(ssp, row0, fq, rs);
	v_add_f32_e32 v166, v161, v167
	v_pk_add_f32 v[160:161], v[186:187], v[190:191]
	v_add_f32_e32 v162, v164, v165
	v_add_f32_e32 v164, v168, v169
	v_add_f32_e32 v165, v170, v171
	v_add_f32_e32 v160, v160, v161
	v_mov_b32_e32 v236, v162
	v_mov_b32_e32 v237, v162
	s_nop 1
	v_permlane16_swap_b32_e32 v236, v237
	v_cndmask_b32_e64 v168, v237, v236, s[98:99]
	v_mov_b32_e32 v236, v163
	v_mov_b32_e32 v237, v163
	s_nop 1
	v_permlane16_swap_b32_e32 v236, v237
	v_cndmask_b32_e64 v169, v237, v236, s[98:99]
	v_mov_b32_e32 v236, v164
	v_mov_b32_e32 v237, v164
	s_nop 1
	v_permlane16_swap_b32_e32 v236, v237
	v_cndmask_b32_e64 v170, v237, v236, s[98:99]
	v_mov_b32_e32 v236, v165
	v_mov_b32_e32 v237, v165
	s_nop 1
	v_permlane16_swap_b32_e32 v236, v237
	v_cndmask_b32_e64 v171, v237, v236, s[98:99]
	v_mov_b32_e32 v236, v160
	v_mov_b32_e32 v237, v160
	s_nop 1
	v_permlane16_swap_b32_e32 v236, v237
	v_cndmask_b32_e64 v136, v237, v236, s[98:99]
	s_waitcnt lgkmcnt(4)
	v_add_f32_e32 v162, v162, v168
	s_waitcnt lgkmcnt(3)
	v_add_f32_e32 v163, v163, v169
	s_waitcnt lgkmcnt(2)
	v_add_f32_e32 v161, v164, v170
	s_waitcnt lgkmcnt(1)
	v_add_f32_e32 v165, v165, v171
	s_waitcnt lgkmcnt(0)
	v_add_f32_e32 v136, v160, v136
	v_mov_b32_e32 v236, v162
	v_mov_b32_e32 v237, v162
	s_nop 1
	v_permlane32_swap_b32_e32 v236, v237
	v_cndmask_b32_e64 v168, v237, v236, s[100:101]
	v_mov_b32_e32 v236, v163
	v_mov_b32_e32 v237, v163
	s_nop 1
	v_permlane32_swap_b32_e32 v236, v237
	v_cndmask_b32_e64 v169, v237, v236, s[100:101]
	v_mov_b32_e32 v236, v161
	v_mov_b32_e32 v237, v161
	s_nop 1
	v_permlane32_swap_b32_e32 v236, v237
	v_cndmask_b32_e64 v164, v237, v236, s[100:101]
	v_mov_b32_e32 v236, v165
	v_mov_b32_e32 v237, v165
	s_nop 1
	v_permlane32_swap_b32_e32 v236, v237
	v_cndmask_b32_e64 v167, v237, v236, s[100:101]
	v_mov_b32_e32 v236, v136
	v_mov_b32_e32 v237, v136
	s_nop 1
	v_permlane32_swap_b32_e32 v236, v237
	v_cndmask_b32_e64 v147, v237, v236, s[100:101]
	s_waitcnt lgkmcnt(4)
	v_add_f32_e32 v160, v162, v168
	s_waitcnt lgkmcnt(3)
	v_add_f32_e32 v162, v163, v169
	s_waitcnt lgkmcnt(2)
	v_add_f32_e32 v161, v161, v164
	s_waitcnt lgkmcnt(1)
	v_add_f32_e32 v163, v165, v167
	s_waitcnt lgkmcnt(0)
	v_add_f32_e32 v136, v136, v147
	v_fmamk_f32 v147, v149, 0x3a800000, v157
	v_rsq_f32_e32 v164, v147
	v_fmamk_f32 v147, v159, 0x3a800000, v157
	v_rsq_f32_e32 v165, v147
	v_fmamk_f32 v147, v166, 0x3a800000, v157
	v_rsq_f32_e32 v166, v147
	v_fmamk_f32 v147, v160, 0x3a800000, v157
	v_rsq_f32_e32 v167, v147
	v_fmamk_f32 v147, v162, 0x3a800000, v157
	v_rsq_f32_e32 v168, v147
	v_fmamk_f32 v147, v161, 0x3a800000, v157
	v_rsq_f32_e32 v160, v147
	v_fmamk_f32 v147, v163, 0x3a800000, v157
	v_fmamk_f32 v136, v136, 0x3a800000, v157
	v_rsq_f32_e32 v159, v147
	v_rsq_f32_e32 v147, v136
	v_mov_b32_e32 v240, v164
	v_mov_b32_e32 v241, v165
	v_mov_b32_e32 v242, v166
	v_mov_b32_e32 v243, v167
	v_mov_b32_e32 v244, v168
	v_mov_b32_e32 v245, v160
	v_mov_b32_e32 v246, v159
	v_mov_b32_e32 v247, v147
	v_mov_b32_e32 v248, s41
	s_branch rsc_join_1
rsc_hit_1:
	s_lshl_b32 s2, s41, 8
	s_add_i32 s2, s2, s29
	v_or_b32_e32 v146, s2, v150
	v_add_u32_e32 v146, 0x80, v146
	v_pk_mul_f32 v[120:121], v[124:125], v[120:121]
	v_pk_mul_f32 v[122:123], v[126:127], v[122:123]
	v_pk_mul_f32 v[112:113], v[116:117], v[112:113]
	v_pk_mul_f32 v[114:115], v[118:119], v[114:115]
	v_pk_mul_f32 v[104:105], v[108:109], v[104:105]
	s_ashr_i32 s3, s2, 13
	s_mul_hi_i32 s11, s3, 0x4400000
	s_mul_i32 s3, s3, 0x4400000
	v_readlane_b32 s16, v235, 44
	v_lshl_or_b32 v148, s42, 7, v152
	v_readlane_b32 s17, v235, 45
	v_pk_mul_f32 v[106:107], v[110:111], v[106:107]
	v_pk_mul_f32 v[96:97], v[100:101], v[96:97]
	v_pk_mul_f32 v[98:99], v[102:103], v[98:99]
	v_pk_mul_f32 v[88:89], v[92:93], v[88:89]
	v_pk_mul_f32 v[90:91], v[94:95], v[90:91]
	v_pk_mul_f32 v[80:81], v[84:85], v[80:81]
	v_pk_mul_f32 v[82:83], v[86:87], v[82:83]
	v_pk_mul_f32 v[72:73], v[76:77], v[72:73]
	v_pk_mul_f32 v[74:75], v[78:79], v[74:75]
	v_pk_mul_f32 v[64:65], v[68:69], v[64:65]
	v_pk_mul_f32 v[66:67], v[70:71], v[66:67]
	v_pk_mul_f32 v[56:57], v[60:61], v[56:57]
	v_pk_mul_f32 v[58:59], v[62:63], v[58:59]
	v_pk_mul_f32 v[48:49], v[52:53], v[48:49]
	v_pk_mul_f32 v[50:51], v[54:55], v[50:51]
	v_pk_mul_f32 v[40:41], v[44:45], v[40:41]
	v_pk_mul_f32 v[42:43], v[46:47], v[42:43]
	v_pk_mul_f32 v[32:33], v[36:37], v[32:33]
	v_pk_mul_f32 v[34:35], v[38:39], v[34:35]
	v_pk_mul_f32 v[24:25], v[28:29], v[24:25]
	v_pk_mul_f32 v[26:27], v[30:31], v[26:27]
	v_pk_mul_f32 v[16:17], v[20:21], v[16:17]
	v_pk_mul_f32 v[18:19], v[22:23], v[18:19]
	v_pk_mul_f32 v[8:9], v[12:13], v[8:9]
	v_pk_mul_f32 v[10:11], v[14:15], v[10:11]
	v_pk_mul_f32 v[0:1], v[4:5], v[0:1]
	v_pk_mul_f32 v[2:3], v[6:7], v[2:3]
	s_waitcnt vmcnt(0)
	v_mov_b32_e32 v164, v240
	v_mov_b32_e32 v165, v241
	v_mov_b32_e32 v166, v242
	v_mov_b32_e32 v167, v243
	v_mov_b32_e32 v168, v244
	v_mov_b32_e32 v160, v245
	v_mov_b32_e32 v159, v246
	v_mov_b32_e32 v147, v247
	s_waitcnt lgkmcnt(0)
; __device__ __forceinline__ unsigned cvt_pk_bf16(float lo, float hi) { unsigned r; asm volatile("v_cvt_pk_bf16_f32 %0, %1, %2" : "=v"(r) : "v"(lo), "v"(hi)); return r; }
;     __device__ __forceinline__ void operator()(const f32x4 (&acc)[2][2][4][2], const Unit& u, int wr, int wc, int fr, int fq) const {
;     ...
;                 const int row = row0 + ai * HALF + m * 16; const float r = rs[ai][m];
;                 const float nrl = r * -1.44269504089f, r2 = r * r;
;                 unsigned pk[4];
; #pragma unroll
;                 for (int q = 0; q < 4; ++q) {
;                     const f32x4 ga = acc[ai][0][m][q >> 1], ua = acc[ai][1][m][q >> 1]; const int e0 = 2 * (q & 1);
;                     const f32x2 g = (f32x2){ga[e0], ga[e0 + 1]}, up = (f32x2){ua[e0], ua[e0 + 1]};
;                     const f32x2 t = g * nrl; f32x2 ex; ex.x = __builtin_amdgcn_exp2f(t.x); ex.y = __builtin_amdgcn_exp2f(t.y);
;                     const f32x2 d = ex + 1.0f; f32x2 rc; rc.x = __builtin_amdgcn_rcpf(d.x); rc.y = __builtin_amdgcn_rcpf(d.y);
;                     const f32x2 o = (g * up) * (rc * r2);
;                     pk[q] = cvt_pk_bf16(o.x, o.y);
;                 }
;                 u32x4 w; w.x = pk[0]; w.y = pk[1]; w.z = pk[2]; w.w = pk[3];
;                 *(u32x4*)(U + (size_t)(row >> 13) * U_SLAB + (size_t)(row & (SEQ - 1)) * U_PITCH + col0) = w;
rsc_join_1:
	v_mul_f32_e32 v136, 0xbfb8aa3b, v164
	v_pk_mul_f32 v[162:163], v[124:125], v[136:137] op_sel_hi:[1,0]
	v_pk_mul_f32 v[124:125], v[126:127], v[136:137] op_sel_hi:[1,0]
	v_exp_f32_e32 v162, v162
	v_exp_f32_e32 v163, v163
	v_exp_f32_e32 v124, v124
	v_exp_f32_e32 v125, v125
	v_mul_f32_e32 v164, v164, v164
	v_pk_add_f32 v[162:163], v[162:163], 1.0 op_sel_hi:[1,0]
	v_bitop3_b32 v161, s2, v158, v150 bitop3:0xc8
	v_rcp_f32_e32 v162, v162
	v_rcp_f32_e32 v163, v163
	v_pk_add_f32 v[124:125], v[124:125], 1.0 op_sel_hi:[1,0]
	s_add_u32 s2, s16, s3
	v_rcp_f32_e32 v124, v124
	v_rcp_f32_e32 v125, v125
	v_pk_mul_f32 v[126:127], v[164:165], v[162:163] op_sel_hi:[0,1]
	v_pk_mul_f32 v[120:121], v[120:121], v[126:127]
	v_pk_mul_f32 v[126:127], v[116:117], v[136:137] op_sel_hi:[1,0]
	v_pk_mul_f32 v[124:125], v[164:165], v[124:125] op_sel_hi:[0,1]
	v_exp_f32_e32 v126, v126
	v_exp_f32_e32 v127, v127
	v_pk_mul_f32 v[122:123], v[122:123], v[124:125]
	v_pk_mul_f32 v[124:125], v[118:119], v[136:137] op_sel_hi:[1,0]
	v_cvt_pk_bf16_f32 v120, v120, v121
	v_cvt_pk_bf16_f32 v121, v122, v123
	v_pk_add_f32 v[122:123], v[126:127], 1.0 op_sel_hi:[1,0]
	v_exp_f32_e32 v124, v124
	v_exp_f32_e32 v125, v125
	v_rcp_f32_e32 v122, v122
	v_rcp_f32_e32 v123, v123
	v_ashrrev_i32_e32 v149, 31, v148
	v_pk_add_f32 v[116:117], v[124:125], 1.0 op_sel_hi:[1,0]
	s_addc_u32 s3, s17, s11
	v_rcp_f32_e32 v116, v116
	v_rcp_f32_e32 v117, v117
	v_pk_mul_f32 v[118:119], v[164:165], v[122:123] op_sel_hi:[0,1]
	v_pk_mul_f32 v[112:113], v[112:113], v[118:119]
	s_nop 0
	v_cvt_pk_bf16_f32 v122, v112, v113
	v_pk_mul_f32 v[112:113], v[164:165], v[116:117] op_sel_hi:[0,1]
	v_mul_f32_e32 v116, 0xbfb8aa3b, v165
	v_pk_mul_f32 v[118:119], v[108:109], v[116:117] op_sel_hi:[1,0]
	v_pk_mul_f32 v[108:109], v[110:111], v[116:117] op_sel_hi:[1,0]
	v_exp_f32_e32 v118, v118
	v_exp_f32_e32 v119, v119
	v_exp_f32_e32 v108, v108
	v_exp_f32_e32 v109, v109
	v_pk_mul_f32 v[112:113], v[114:115], v[112:113]
	v_pk_add_f32 v[118:119], v[118:119], 1.0 op_sel_hi:[1,0]
	v_cvt_pk_bf16_f32 v123, v112, v113
	v_mul_u32_u24_e32 v112, 0xb40, v161
	v_lshlrev_b32_e32 v136, 1, v112
	v_rcp_f32_e32 v118, v118
	v_rcp_f32_e32 v119, v119
	v_lshl_add_u64 v[114:115], s[2:3], 0, v[136:137]
	v_lshlrev_b64 v[112:113], 1, v[148:149]
	v_pk_add_f32 v[108:109], v[108:109], 1.0 op_sel_hi:[1,0]
	v_lshl_add_u64 v[114:115], v[114:115], 0, v[112:113]
	v_rcp_f32_e32 v108, v108
	v_rcp_f32_e32 v109, v109
	global_store_dwordx4 v[114:115], v[120:123], off
	s_nop 1
	v_mul_f32_e32 v120, v165, v165
	v_pk_mul_f32 v[110:111], v[120:121], v[118:119] op_sel_hi:[0,1]
	v_pk_mul_f32 v[104:105], v[104:105], v[110:111]
	v_pk_mul_f32 v[110:111], v[100:101], v[116:117] op_sel_hi:[1,0]
	v_pk_mul_f32 v[108:109], v[120:121], v[108:109] op_sel_hi:[0,1]
	v_exp_f32_e32 v110, v110
	v_exp_f32_e32 v111, v111
	v_pk_mul_f32 v[106:107], v[106:107], v[108:109]
	v_pk_mul_f32 v[108:109], v[102:103], v[116:117] op_sel_hi:[1,0]
	v_cvt_pk_bf16_f32 v104, v104, v105
	v_cvt_pk_bf16_f32 v105, v106, v107
	v_pk_add_f32 v[106:107], v[110:111], 1.0 op_sel_hi:[1,0]
	v_exp_f32_e32 v108, v108
	v_exp_f32_e32 v109, v109
	v_rcp_f32_e32 v106, v106
	v_rcp_f32_e32 v107, v107
	v_pk_add_f32 v[100:101], v[108:109], 1.0 op_sel_hi:[1,0]
	s_nop 0
	v_rcp_f32_e32 v100, v100
	v_rcp_f32_e32 v101, v101
	v_pk_mul_f32 v[102:103], v[120:121], v[106:107] op_sel_hi:[0,1]
	v_pk_mul_f32 v[96:97], v[96:97], v[102:103]
	s_nop 0
	v_cvt_pk_bf16_f32 v106, v96, v97
	v_pk_mul_f32 v[96:97], v[120:121], v[100:101] op_sel_hi:[0,1]
	v_pk_mul_f32 v[96:97], v[98:99], v[96:97]
	v_add_co_u32_e32 v100, vcc, s28, v114
	v_cvt_pk_bf16_f32 v107, v96, v97
	v_mul_f32_e32 v96, 0xbfb8aa3b, v166
	v_pk_mul_f32 v[98:99], v[92:93], v[96:97] op_sel_hi:[1,0]
	v_pk_mul_f32 v[92:93], v[94:95], v[96:97] op_sel_hi:[1,0]
	v_exp_f32_e32 v98, v98
	v_exp_f32_e32 v99, v99
	v_exp_f32_e32 v92, v92
	v_exp_f32_e32 v93, v93
	v_addc_co_u32_e32 v101, vcc, 0, v115, vcc
	v_pk_add_f32 v[98:99], v[98:99], 1.0 op_sel_hi:[1,0]
	v_pk_add_f32 v[92:93], v[92:93], 1.0 op_sel_hi:[1,0]
	v_rcp_f32_e32 v98, v98
	v_rcp_f32_e32 v99, v99
	v_rcp_f32_e32 v92, v92
	v_rcp_f32_e32 v93, v93
	global_store_dwordx4 v[100:101], v[104:107], off offset:2048
	v_mul_f32_e32 v100, v166, v166
	v_pk_mul_f32 v[94:95], v[100:101], v[98:99] op_sel_hi:[0,1]
	v_pk_mul_f32 v[88:89], v[88:89], v[94:95]
	v_pk_mul_f32 v[94:95], v[84:85], v[96:97] op_sel_hi:[1,0]
	v_pk_mul_f32 v[92:93], v[100:101], v[92:93] op_sel_hi:[0,1]
	v_exp_f32_e32 v94, v94
	v_exp_f32_e32 v95, v95
	v_pk_mul_f32 v[90:91], v[90:91], v[92:93]
	v_pk_mul_f32 v[92:93], v[86:87], v[96:97] op_sel_hi:[1,0]
	v_cvt_pk_bf16_f32 v88, v88, v89
	v_cvt_pk_bf16_f32 v89, v90, v91
	v_pk_add_f32 v[90:91], v[94:95], 1.0 op_sel_hi:[1,0]
	v_exp_f32_e32 v92, v92
	v_exp_f32_e32 v93, v93
	v_rcp_f32_e32 v90, v90
	v_rcp_f32_e32 v91, v91
	v_pk_add_f32 v[84:85], v[92:93], 1.0 op_sel_hi:[1,0]
	s_nop 0
	v_rcp_f32_e32 v84, v84
	v_rcp_f32_e32 v85, v85
	v_pk_mul_f32 v[86:87], v[100:101], v[90:91] op_sel_hi:[0,1]
	v_pk_mul_f32 v[80:81], v[80:81], v[86:87]
	s_nop 0
	v_cvt_pk_bf16_f32 v90, v80, v81
	v_pk_mul_f32 v[80:81], v[100:101], v[84:85] op_sel_hi:[0,1]
	v_pk_mul_f32 v[80:81], v[82:83], v[80:81]
	v_add_co_u32_e32 v84, vcc, s38, v114
	v_cvt_pk_bf16_f32 v91, v80, v81
	v_mul_f32_e32 v80, 0xbfb8aa3b, v167
	v_pk_mul_f32 v[82:83], v[76:77], v[80:81] op_sel_hi:[1,0]
	v_pk_mul_f32 v[76:77], v[78:79], v[80:81] op_sel_hi:[1,0]
	v_exp_f32_e32 v82, v82
	v_exp_f32_e32 v83, v83
	v_exp_f32_e32 v76, v76
	v_exp_f32_e32 v77, v77
	v_addc_co_u32_e32 v85, vcc, 0, v115, vcc
	v_pk_add_f32 v[82:83], v[82:83], 1.0 op_sel_hi:[1,0]
	v_pk_add_f32 v[76:77], v[76:77], 1.0 op_sel_hi:[1,0]
; __device__ __forceinline__ unsigned cvt_pk_bf16(float lo, float hi) { unsigned r; asm volatile("v_cvt_pk_bf16_f32 %0, %1, %2" : "=v"(r) : "v"(lo), "v"(hi)); return r; }
;     __device__ __forceinline__ void operator()(const f32x4 (&acc)[2][2][4][2], const Unit& u, int wr, int wc, int fr, int fq) const {
;     ...
;                 const int row = row0 + ai * HALF + m * 16; const float r = rs[ai][m];
;                 const float nrl = r * -1.44269504089f, r2 = r * r;
;                 unsigned pk[4];
; #pragma unroll
;                 for (int q = 0; q < 4; ++q) {
;                     const f32x4 ga = acc[ai][0][m][q >> 1], ua = acc[ai][1][m][q >> 1]; const int e0 = 2 * (q & 1);
;                     const f32x2 g = (f32x2){ga[e0], ga[e0 + 1]}, up = (f32x2){ua[e0], ua[e0 + 1]};
;                     const f32x2 t = g * nrl; f32x2 ex; ex.x = __builtin_amdgcn_exp2f(t.x); ex.y = __builtin_amdgcn_exp2f(t.y);
;                     const f32x2 d = ex + 1.0f; f32x2 rc; rc.x = __builtin_amdgcn_rcpf(d.x); rc.y = __builtin_amdgcn_rcpf(d.y);
;                     const f32x2 o = (g * up) * (rc * r2);
;                     pk[q] = cvt_pk_bf16(o.x, o.y);
;                 }
;                 u32x4 w; w.x = pk[0]; w.y = pk[1]; w.z = pk[2]; w.w = pk[3];
;                 *(u32x4*)(U + (size_t)(row >> 13) * U_SLAB + (size_t)(row & (SEQ - 1)) * U_PITCH + col0) = w;
	v_rcp_f32_e32 v82, v82
	v_rcp_f32_e32 v83, v83
	v_rcp_f32_e32 v76, v76
	v_rcp_f32_e32 v77, v77
	global_store_dwordx4 v[84:85], v[88:91], off
	v_mul_f32_e32 v84, v167, v167
	v_pk_mul_f32 v[78:79], v[84:85], v[82:83] op_sel_hi:[0,1]
	v_pk_mul_f32 v[72:73], v[72:73], v[78:79]
	v_pk_mul_f32 v[78:79], v[68:69], v[80:81] op_sel_hi:[1,0]
	v_pk_mul_f32 v[76:77], v[84:85], v[76:77] op_sel_hi:[0,1]
	v_exp_f32_e32 v78, v78
	v_exp_f32_e32 v79, v79
	v_pk_mul_f32 v[74:75], v[74:75], v[76:77]
	v_pk_mul_f32 v[76:77], v[70:71], v[80:81] op_sel_hi:[1,0]
	v_cvt_pk_bf16_f32 v72, v72, v73
	v_cvt_pk_bf16_f32 v73, v74, v75
	v_pk_add_f32 v[74:75], v[78:79], 1.0 op_sel_hi:[1,0]
	v_exp_f32_e32 v76, v76
	v_exp_f32_e32 v77, v77
	v_rcp_f32_e32 v74, v74
	v_rcp_f32_e32 v75, v75
	v_pk_add_f32 v[68:69], v[76:77], 1.0 op_sel_hi:[1,0]
	s_nop 0
	v_rcp_f32_e32 v68, v68
	v_rcp_f32_e32 v69, v69
	v_pk_mul_f32 v[70:71], v[84:85], v[74:75] op_sel_hi:[0,1]
	v_pk_mul_f32 v[64:65], v[64:65], v[70:71]
	s_nop 0
	v_cvt_pk_bf16_f32 v74, v64, v65
	v_pk_mul_f32 v[64:65], v[84:85], v[68:69] op_sel_hi:[0,1]
	v_pk_mul_f32 v[64:65], v[66:67], v[64:65]
	v_and_b32_e32 v69, 0x1fcf, v146
	v_cvt_pk_bf16_f32 v75, v64, v65
	v_add_co_u32_e32 v64, vcc, s39, v114
	v_mul_f32_e32 v68, v168, v168
	s_nop 0
	v_addc_co_u32_e32 v65, vcc, 0, v115, vcc
	global_store_dwordx4 v[64:65], v[72:75], off offset:2048
	v_mul_f32_e32 v64, 0xbfb8aa3b, v168
	v_pk_mul_f32 v[66:67], v[60:61], v[64:65] op_sel_hi:[1,0]
	v_ashrrev_i32_e32 v65, 13, v146
	v_exp_f32_e32 v66, v66
	v_exp_f32_e32 v67, v67
	v_pk_mul_f32 v[60:61], v[62:63], v[64:65] op_sel_hi:[1,0]
	v_pk_add_f32 v[66:67], v[66:67], 1.0 op_sel_hi:[1,0]
	v_exp_f32_e32 v60, v60
	v_exp_f32_e32 v61, v61
	v_rcp_f32_e32 v66, v66
	v_rcp_f32_e32 v67, v67
	v_pk_add_f32 v[60:61], v[60:61], 1.0 op_sel_hi:[1,0]
	s_nop 0
	v_rcp_f32_e32 v60, v60
	v_rcp_f32_e32 v61, v61
	v_pk_mul_f32 v[62:63], v[68:69], v[66:67] op_sel_hi:[0,1]
	v_pk_mul_f32 v[56:57], v[56:57], v[62:63]
	v_pk_mul_f32 v[62:63], v[52:53], v[64:65] op_sel_hi:[1,0]
	v_pk_mul_f32 v[60:61], v[68:69], v[60:61] op_sel_hi:[0,1]
	v_exp_f32_e32 v62, v62
	v_exp_f32_e32 v63, v63
	v_pk_mul_f32 v[58:59], v[58:59], v[60:61]
	v_pk_mul_f32 v[60:61], v[54:55], v[64:65] op_sel_hi:[1,0]
	v_cvt_pk_bf16_f32 v56, v56, v57
	v_cvt_pk_bf16_f32 v57, v58, v59
	v_pk_add_f32 v[58:59], v[62:63], 1.0 op_sel_hi:[1,0]
	v_exp_f32_e32 v60, v60
	v_exp_f32_e32 v61, v61
	v_rcp_f32_e32 v58, v58
	v_rcp_f32_e32 v59, v59
	v_pk_add_f32 v[52:53], v[60:61], 1.0 op_sel_hi:[1,0]
	s_nop 0
	v_rcp_f32_e32 v52, v52
	v_rcp_f32_e32 v53, v53
	v_pk_mul_f32 v[54:55], v[68:69], v[58:59] op_sel_hi:[0,1]
	v_pk_mul_f32 v[48:49], v[48:49], v[54:55]
	v_mul_f32_e32 v54, v160, v160
	v_cvt_pk_bf16_f32 v58, v48, v49
	v_pk_mul_f32 v[48:49], v[68:69], v[52:53] op_sel_hi:[0,1]
	v_pk_mul_f32 v[48:49], v[50:51], v[48:49]
	v_mul_u32_u24_e32 v50, 0xb40, v69
	v_lshlrev_b32_e32 v136, 1, v50
	v_mul_f32_e32 v50, 0xbfb8aa3b, v160
	v_pk_mul_f32 v[52:53], v[44:45], v[50:51] op_sel_hi:[1,0]
	v_pk_mul_f32 v[44:45], v[46:47], v[50:51] op_sel_hi:[1,0]
	v_exp_f32_e32 v52, v52
	v_exp_f32_e32 v53, v53
	v_exp_f32_e32 v44, v44
	v_exp_f32_e32 v45, v45
	v_cvt_pk_bf16_f32 v59, v48, v49
	v_pk_add_f32 v[52:53], v[52:53], 1.0 op_sel_hi:[1,0]
	v_mov_b64_e32 v[48:49], s[16:17]
	v_rcp_f32_e32 v52, v52
	v_rcp_f32_e32 v53, v53
	v_pk_add_f32 v[44:45], v[44:45], 1.0 op_sel_hi:[1,0]
	v_mad_i64_i32 v[48:49], s[2:3], v65, s37, v[48:49]
	v_rcp_f32_e32 v44, v44
	v_rcp_f32_e32 v45, v45
	v_pk_mul_f32 v[46:47], v[54:55], v[52:53] op_sel_hi:[0,1]
	v_pk_mul_f32 v[40:41], v[40:41], v[46:47]
	v_pk_mul_f32 v[46:47], v[36:37], v[50:51] op_sel_hi:[1,0]
	v_pk_mul_f32 v[44:45], v[54:55], v[44:45] op_sel_hi:[0,1]
	v_exp_f32_e32 v46, v46
	v_exp_f32_e32 v47, v47
	v_pk_mul_f32 v[42:43], v[42:43], v[44:45]
	v_pk_mul_f32 v[44:45], v[38:39], v[50:51] op_sel_hi:[1,0]
	v_lshl_add_u64 v[48:49], v[48:49], 0, v[136:137]
	v_exp_f32_e32 v44, v44
	v_exp_f32_e32 v45, v45
	v_lshl_add_u64 v[48:49], v[48:49], 0, v[112:113]
	global_store_dwordx4 v[48:49], v[56:59], off
; __device__ __forceinline__ unsigned cvt_pk_bf16(float lo, float hi) { unsigned r; asm volatile("v_cvt_pk_bf16_f32 %0, %1, %2" : "=v"(r) : "v"(lo), "v"(hi)); return r; }
; #define PG8_BAR __builtin_amdgcn_s_barrier()
;     __device__ __forceinline__ void operator()(const f32x4 (&acc)[2][2][4][2], const Unit& u, int wr, int wc, int fr, int fq) const {
;     ...
;                 for (int q = 0; q < 4; ++q) {
;                     const f32x4 ga = acc[ai][0][m][q >> 1], ua = acc[ai][1][m][q >> 1]; const int e0 = 2 * (q & 1);
;                     const f32x2 g = (f32x2){ga[e0], ga[e0 + 1]}, up = (f32x2){ua[e0], ua[e0 + 1]};
;                     const f32x2 t = g * nrl; f32x2 ex; ex.x = __builtin_amdgcn_exp2f(t.x); ex.y = __builtin_amdgcn_exp2f(t.y);
;                     const f32x2 d = ex + 1.0f; f32x2 rc; rc.x = __builtin_amdgcn_rcpf(d.x); rc.y = __builtin_amdgcn_rcpf(d.y);
;                     const f32x2 o = (g * up) * (rc * r2);
;                     pk[q] = cvt_pk_bf16(o.x, o.y);
;                 }
;                 u32x4 w; w.x = pk[0]; w.y = pk[1]; w.z = pk[2]; w.w = pk[3];
;                 *(u32x4*)(U + (size_t)(row >> 13) * U_SLAB + (size_t)(row & (SEQ - 1)) * U_PITCH + col0) = w;
; template <class Epi>
; __device__ __forceinline__ void gemm_phase(LAS unsigned char* lds, const Gemm g, const StaticOrder& S, const Epi& E) {
;     ...
;         if (wr == 0) PG8_BAR;
;         E(acc, cur, wr, wc, fr, fq);
;         if (!has_next) break;
; #pragma unroll
;         for (int a = 0; a < 2; ++a)
; #pragma unroll
;             for (int b = 0; b < 2; ++b)
; #pragma unroll
;                 for (int m = 0; m < 4; ++m)
; #pragma unroll
;                     for (int n = 0; n < 2; ++n) acc[a][b][m][n] = (f32x4){0.f, 0.f, 0.f, 0.f};
;         cur = nxt; cA = nA; cB = nB; ++ui;
;         if (wr == 1) PG8_BAR;
	v_cvt_pk_bf16_f32 v40, v40, v41
	v_cvt_pk_bf16_f32 v41, v42, v43
	v_pk_add_f32 v[42:43], v[46:47], 1.0 op_sel_hi:[1,0]
	v_pk_add_f32 v[36:37], v[44:45], 1.0 op_sel_hi:[1,0]
	v_rcp_f32_e32 v42, v42
	v_rcp_f32_e32 v43, v43
	v_rcp_f32_e32 v36, v36
	v_rcp_f32_e32 v37, v37
	s_mov_b64 s[2:3], -1
	v_pk_mul_f32 v[38:39], v[54:55], v[42:43] op_sel_hi:[0,1]
	v_pk_mul_f32 v[32:33], v[32:33], v[38:39]
	s_nop 0
	v_cvt_pk_bf16_f32 v42, v32, v33
	v_pk_mul_f32 v[32:33], v[54:55], v[36:37] op_sel_hi:[0,1]
	v_pk_mul_f32 v[32:33], v[34:35], v[32:33]
	v_add_co_u32_e32 v36, vcc, s28, v48
	v_cvt_pk_bf16_f32 v43, v32, v33
	v_mul_f32_e32 v32, 0xbfb8aa3b, v159
	v_pk_mul_f32 v[34:35], v[28:29], v[32:33] op_sel_hi:[1,0]
	v_pk_mul_f32 v[28:29], v[30:31], v[32:33] op_sel_hi:[1,0]
	v_exp_f32_e32 v34, v34
	v_exp_f32_e32 v35, v35
	v_exp_f32_e32 v28, v28
	v_exp_f32_e32 v29, v29
	v_addc_co_u32_e32 v37, vcc, 0, v49, vcc
	v_pk_add_f32 v[34:35], v[34:35], 1.0 op_sel_hi:[1,0]
	v_pk_add_f32 v[28:29], v[28:29], 1.0 op_sel_hi:[1,0]
	v_rcp_f32_e32 v34, v34
	v_rcp_f32_e32 v35, v35
	v_rcp_f32_e32 v28, v28
	v_rcp_f32_e32 v29, v29
	global_store_dwordx4 v[36:37], v[40:43], off offset:2048
	v_mul_f32_e32 v36, v159, v159
	v_pk_mul_f32 v[30:31], v[36:37], v[34:35] op_sel_hi:[0,1]
	v_pk_mul_f32 v[24:25], v[24:25], v[30:31]
	v_pk_mul_f32 v[30:31], v[20:21], v[32:33] op_sel_hi:[1,0]
	v_pk_mul_f32 v[28:29], v[36:37], v[28:29] op_sel_hi:[0,1]
	v_exp_f32_e32 v30, v30
	v_exp_f32_e32 v31, v31
	v_pk_mul_f32 v[26:27], v[26:27], v[28:29]
	v_pk_mul_f32 v[28:29], v[22:23], v[32:33] op_sel_hi:[1,0]
	v_cvt_pk_bf16_f32 v24, v24, v25
	v_cvt_pk_bf16_f32 v25, v26, v27
	v_pk_add_f32 v[26:27], v[30:31], 1.0 op_sel_hi:[1,0]
	v_exp_f32_e32 v28, v28
	v_exp_f32_e32 v29, v29
	v_rcp_f32_e32 v26, v26
	v_rcp_f32_e32 v27, v27
	v_pk_add_f32 v[20:21], v[28:29], 1.0 op_sel_hi:[1,0]
	s_nop 0
	v_rcp_f32_e32 v20, v20
	v_rcp_f32_e32 v21, v21
	v_pk_mul_f32 v[22:23], v[36:37], v[26:27] op_sel_hi:[0,1]
	v_pk_mul_f32 v[16:17], v[16:17], v[22:23]
	s_nop 0
	v_cvt_pk_bf16_f32 v26, v16, v17
	v_pk_mul_f32 v[16:17], v[36:37], v[20:21] op_sel_hi:[0,1]
	v_pk_mul_f32 v[16:17], v[18:19], v[16:17]
	v_add_co_u32_e32 v20, vcc, s38, v48
	v_cvt_pk_bf16_f32 v27, v16, v17
	v_mul_f32_e32 v16, 0xbfb8aa3b, v147
	v_pk_mul_f32 v[18:19], v[12:13], v[16:17] op_sel_hi:[1,0]
	v_pk_mul_f32 v[12:13], v[14:15], v[16:17] op_sel_hi:[1,0]
	v_exp_f32_e32 v18, v18
	v_exp_f32_e32 v19, v19
	v_exp_f32_e32 v12, v12
	v_exp_f32_e32 v13, v13
	v_addc_co_u32_e32 v21, vcc, 0, v49, vcc
	v_pk_add_f32 v[18:19], v[18:19], 1.0 op_sel_hi:[1,0]
	v_pk_add_f32 v[12:13], v[12:13], 1.0 op_sel_hi:[1,0]
	v_rcp_f32_e32 v18, v18
	v_rcp_f32_e32 v19, v19
	v_rcp_f32_e32 v12, v12
	v_rcp_f32_e32 v13, v13
	global_store_dwordx4 v[20:21], v[24:27], off
	v_mul_f32_e32 v20, v147, v147
	v_pk_mul_f32 v[14:15], v[20:21], v[18:19] op_sel_hi:[0,1]
	v_pk_mul_f32 v[8:9], v[8:9], v[14:15]
	v_pk_mul_f32 v[14:15], v[4:5], v[16:17] op_sel_hi:[1,0]
	v_pk_mul_f32 v[12:13], v[20:21], v[12:13] op_sel_hi:[0,1]
	v_exp_f32_e32 v14, v14
	v_exp_f32_e32 v15, v15
	v_pk_mul_f32 v[10:11], v[10:11], v[12:13]
	v_pk_mul_f32 v[12:13], v[6:7], v[16:17] op_sel_hi:[1,0]
	v_cvt_pk_bf16_f32 v8, v8, v9
	v_cvt_pk_bf16_f32 v9, v10, v11
	v_pk_add_f32 v[10:11], v[14:15], 1.0 op_sel_hi:[1,0]
	v_exp_f32_e32 v12, v12
	v_exp_f32_e32 v13, v13
	v_rcp_f32_e32 v10, v10
	v_rcp_f32_e32 v11, v11
	v_pk_add_f32 v[4:5], v[12:13], 1.0 op_sel_hi:[1,0]
	s_nop 0
	v_rcp_f32_e32 v4, v4
	v_rcp_f32_e32 v5, v5
	v_pk_mul_f32 v[6:7], v[20:21], v[10:11] op_sel_hi:[0,1]
	v_pk_mul_f32 v[0:1], v[0:1], v[6:7]
	s_nop 0
	v_cvt_pk_bf16_f32 v10, v0, v1
	v_pk_mul_f32 v[0:1], v[20:21], v[4:5] op_sel_hi:[0,1]
	v_pk_mul_f32 v[0:1], v[2:3], v[0:1]
	s_nop 0
	v_cvt_pk_bf16_f32 v11, v0, v1
	v_add_co_u32_e32 v0, vcc, 0x43000, v48
	s_nop 1
	v_addc_co_u32_e32 v1, vcc, 0, v49, vcc
	s_andn2_b64 vcc, exec, s[4:5]
	global_store_dwordx4 v[0:1], v[8:11], off offset:2048
	s_cbranch_vccnz .LBB0_925
	s_andn2_b64 vcc, exec, s[0:1]
	s_cbranch_vccnz .LBB0_924
	s_barrier
	s_branch .LBB0_924

; __global__ void __launch_bounds__(512, 2) mk_fwd(Args a) {
	.amdhsa_kernel _Z6mk_fwd4Args
		.amdhsa_group_segment_fixed_size 0
		.amdhsa_private_segment_fixed_size 0
		.amdhsa_kernarg_size 408
		.amdhsa_user_sgpr_count 2
		.amdhsa_user_sgpr_dispatch_ptr 0
		.amdhsa_user_sgpr_queue_ptr 0
		.amdhsa_user_sgpr_kernarg_segment_ptr 1
		.amdhsa_user_sgpr_dispatch_id 0
		.amdhsa_user_sgpr_kernarg_preload_length 0
		.amdhsa_user_sgpr_kernarg_preload_offset 0
		.amdhsa_user_sgpr_private_segment_size 0
		.amdhsa_uses_dynamic_stack 0
		.amdhsa_enable_private_segment 0
		.amdhsa_system_sgpr_workgroup_id_x 1
		.amdhsa_system_sgpr_workgroup_id_y 0
		.amdhsa_system_sgpr_workgroup_id_z 0
		.amdhsa_system_sgpr_workgroup_info 0
		.amdhsa_system_vgpr_workitem_id 2
		.amdhsa_next_free_vgpr 256
		.amdhsa_next_free_sgpr 102
		.amdhsa_accum_offset 256
		.amdhsa_reserve_vcc 1
		.amdhsa_float_round_mode_32 0
		.amdhsa_float_round_mode_16_64 0
		.amdhsa_float_denorm_mode_32 3
		.amdhsa_float_denorm_mode_16_64 3
		.amdhsa_dx10_clamp 1
		.amdhsa_ieee_mode 1
		.amdhsa_fp16_overflow 0
		.amdhsa_tg_split 0
		.amdhsa_exception_fp_ieee_invalid_op 0
		.amdhsa_exception_fp_denorm_src 0
		.amdhsa_exception_fp_ieee_div_zero 0
		.amdhsa_exception_fp_ieee_overflow 0
		.amdhsa_exception_fp_ieee_underflow 0
		.amdhsa_exception_fp_ieee_inexact 0
		.amdhsa_exception_int_div_zero 0
	.end_amdhsa_kernel

; __global__ void __launch_bounds__(512, 2) mk_fwd(Args a) {
amdhsa.kernels:
  - .agpr_count:     0
    .args:
      - .offset:         0
        .size:           152
        .value_kind:     by_value
      - .offset:         152
        .size:           4
        .value_kind:     hidden_block_count_x
      - .offset:         156
        .size:           4
        .value_kind:     hidden_block_count_y
      - .offset:         160
        .size:           4
        .value_kind:     hidden_block_count_z
      - .offset:         164
        .size:           2
        .value_kind:     hidden_group_size_x
      - .offset:         166
        .size:           2
        .value_kind:     hidden_group_size_y
      - .offset:         168
        .size:           2
        .value_kind:     hidden_group_size_z
      - .offset:         170
        .size:           2
        .value_kind:     hidden_remainder_x
      - .offset:         172
        .size:           2
        .value_kind:     hidden_remainder_y
      - .offset:         174
        .size:           2
        .value_kind:     hidden_remainder_z
      - .offset:         192
        .size:           8
        .value_kind:     hidden_global_offset_x
      - .offset:         200
        .size:           8
        .value_kind:     hidden_global_offset_y
      - .offset:         208
        .size:           8
        .value_kind:     hidden_global_offset_z
      - .offset:         216
        .size:           2
        .value_kind:     hidden_grid_dims
      - .offset:         240
        .size:           8
        .value_kind:     hidden_multigrid_sync_arg
      - .offset:         272
        .size:           4
        .value_kind:     hidden_dynamic_lds_size
    .group_segment_fixed_size: 0
    .kernarg_segment_align: 8
    .kernarg_segment_size: 408
    .language:       OpenCL C
    .language_version:
      - 2
      - 0
    .max_flat_workgroup_size: 512
    .name:           _Z6mk_fwd4Args
    .private_segment_fixed_size: 0
    .sgpr_count:     108
    .sgpr_spill_count: 94
    .symbol:         _Z6mk_fwd4Args.kd
    .uniform_work_group_size: 1
    .uses_dynamic_stack: false
    .vgpr_count:     256
    .vgpr_spill_count: 0
    .wavefront_size: 64
